# attention A: one v_add3 per K/V fragment address (per-phase lane constant), single-copy cross-half max exchange
# baseline (speedup 1.0000x reference)
.LBB0_335:
	s_cmp_lt_i32 s88, 3
	s_cselect_b64 s[4:5], -1, 0
	s_and_b64 s[2:3], s[4:5], s[2:3]
	s_andn2_b64 vcc, exec, s[2:3]
	s_cbranch_vccnz .LBB0_403
	v_lshrrev_b32_e32 v182, 5, v214
	s_waitcnt lgkmcnt(0)
	v_lshrrev_b32_e32 v4, 1, v215
	v_readlane_b32 s4, v243, 16
	v_bitop3_b32 v4, v182, v4, 7 bitop3:0x78
	s_lshl_b32 s40, s92, 5
	s_lshr_b32 s41, s4, 7
	v_mul_u32_u24_e32 v0, 0xc00, v178
	v_lshlrev_b32_e32 v3, 3, v182
	v_lshlrev_b32_e32 v2, 3, v215
	v_lshlrev_b32_e32 v173, 4, v4
	v_lshlrev_b32_e32 v4, 1, v215
	s_cmpk_gt_i32 s33, 0xff
	v_mov_b32_e32 v1, 0
	s_movk_i32 s42, 0xc00
	v_lshrrev_b32_e32 v172, 3, v214
	v_bfe_u32 v183, v215, 2, 2
	v_lshlrev_b32_e32 v174, 7, v178
	v_and_b32_e32 v175, 32, v4
	v_and_b32_e32 v176, 24, v2
	v_xor_b32_e32 v177, 32, v173
	v_xor_b32_e32 v179, 64, v173
	v_xor_b32_e32 v180, 0x60, v173
	v_lshlrev_b32_e32 v181, 2, v182
	v_lshlrev_b32_e32 v132, 1, v0
	v_lshlrev_b32_e32 v134, 1, v3
	s_cbranch_scc1 .LBB0_377
	v_mov_b32_e32 v0, 0x184000
	global_load_dword v136, v0, s[50:51]
	v_lshrrev_b32_e32 v184, 4, v214
	v_lshlrev_b32_e32 v0, 2, v181
	v_and_b32_e32 v3, 0x78, v2
	v_lshlrev_b32_e32 v5, 5, v184
	v_lshl_add_u64 v[144:145], s[64:65], 0, v[0:1]
	v_mul_u32_u24_e32 v0, 0xc00, v184
	s_movk_i32 s4, 0x78
	s_movk_i32 s24, 0x3000
	v_lshlrev_b32_e32 v187, 6, v183
	v_mbcnt_lo_u32_b32 v4, -1, 0
	v_bitop3_b32 v196, v5, v0, v3 bitop3:0xde
	v_lshlrev_b32_e32 v185, 10, v182
	v_lshlrev_b32_e32 v186, 8, v183
	v_mul_u32_u24_e32 v188, 0xc00, v172
	s_mov_b32 s5, 0
	s_mov_b64 s[6:7], 0x400
	s_mov_b64 s[12:13], 0x800
	v_mov_b32_e32 v133, v1
	v_mov_b32_e32 v135, v1
	s_mov_b64 s[14:15], 0x60000
	s_mov_b64 s[16:17], 0xc0000
	s_mov_b32 s43, 0x3e38aa3b
	s_mov_b64 s[18:19], 0x480
	s_mov_b64 s[20:21], 0x60080
	s_mov_b64 s[22:23], 0xc0080
	v_mov_b32_e32 v189, 0x358637bd
	v_mov_b64_e32 v[138:139], 0x8520800
	v_mov_b64_e32 v[140:141], 0x8520400
	v_mov_b64_e32 v[142:143], 0x8520480
	v_xor_b32_e32 v190, 64, v187
	v_xor_b32_e32 v191, 0x80, v187
	v_xor_b32_e32 v192, 0xc0, v187
	v_add3_u32 v199, v185, v186, v175
	v_add_u32_e32 v199, v199, v176
	v_mbcnt_hi_u32_b32 v193, -1, v4
	v_bitop3_b32 v194, v5, v2, s4 bitop3:0x78
	v_bitop3_b32 v195, v5, s24, v3 bitop3:0xde
	v_add_u32_e32 v197, 0x3000, v196
	s_mov_b32 s44, s33
	s_waitcnt vmcnt(0)
	v_mov_b32_e32 v137, v136
	s_branch .LBB0_339

.LBB0_344:
	v_add3_u32 v248, s38, v199, v187
	v_add3_u32 v249, s38, v199, v190
	v_add3_u32 v250, s38, v199, v191
	v_add3_u32 v251, s38, v199, v192
	ds_read_b64_tr_b16 v[2:3], v248 offset:8192
	ds_read_b64_tr_b16 v[4:5], v248 offset:10240
	ds_read_b64_tr_b16 v[6:7], v249 offset:8192
	ds_read_b64_tr_b16 v[8:9], v249 offset:10240
	ds_read_b64_tr_b16 v[10:11], v250 offset:8192
	ds_read_b64_tr_b16 v[12:13], v250 offset:10240
	ds_read_b64_tr_b16 v[244:245], v251 offset:8192
	ds_read_b64_tr_b16 v[246:247], v251 offset:10240
	v_fma_f32 v96, v96, s43, -v151
	v_exp_f32_e32 v96, v96
	v_fma_f32 v97, v97, s43, -v151
	v_exp_f32_e32 v97, v97
	v_fma_f32 v98, v98, s43, -v151
	v_exp_f32_e32 v98, v98
	v_fma_f32 v99, v99, s43, -v151
	v_exp_f32_e32 v99, v99
	v_fma_f32 v100, v100, s43, -v151
	v_exp_f32_e32 v100, v100
	v_fma_f32 v101, v101, s43, -v151
	v_exp_f32_e32 v101, v101
	v_fma_f32 v102, v102, s43, -v151
	v_exp_f32_e32 v102, v102
	v_fma_f32 v103, v103, s43, -v151
	v_exp_f32_e32 v103, v103
	v_add_f32_e32 v0, v96, v97
	v_add_f32_e32 v14, v98, v99
	v_cvt_pk_bf16_f32 v96, v96, v97
	v_cvt_pk_bf16_f32 v97, v98, v99
	v_cvt_pk_bf16_f32 v98, v100, v101
	v_cvt_pk_bf16_f32 v99, v102, v103
	v_add_f32_e32 v15, v100, v101
	v_add_f32_e32 v0, v0, v102
	v_add_f32_e32 v14, v14, v103
	s_waitcnt lgkmcnt(6)
	v_mfma_f32_32x32x16_bf16 v[64:79], v[2:5], v[96:99], v[64:79]
	ds_read_b64_tr_b16 v[156:157], v248 offset:12288
	ds_read_b64_tr_b16 v[158:159], v248 offset:14336
	ds_read_b64_tr_b16 v[160:161], v249 offset:12288
	ds_read_b64_tr_b16 v[162:163], v249 offset:14336
	ds_read_b64_tr_b16 v[252:253], v250 offset:12288
	ds_read_b64_tr_b16 v[254:255], v250 offset:14336
	ds_read_b64_tr_b16 v[100:101], v251 offset:12288
	ds_read_b64_tr_b16 v[102:103], v251 offset:14336
	v_fma_f32 v104, v104, s43, -v151
	v_exp_f32_e32 v104, v104
	v_fma_f32 v105, v105, s43, -v151
	v_exp_f32_e32 v105, v105
	s_waitcnt lgkmcnt(12)
	v_mfma_f32_32x32x16_bf16 v[48:63], v[6:9], v[96:99], v[48:63]
	v_fma_f32 v106, v106, s43, -v151
	v_exp_f32_e32 v106, v106
	v_fma_f32 v107, v107, s43, -v151
	v_exp_f32_e32 v107, v107
	s_waitcnt lgkmcnt(10)
	v_mfma_f32_32x32x16_bf16 v[32:47], v[10:13], v[96:99], v[32:47]
	v_fma_f32 v108, v108, s43, -v151
	v_exp_f32_e32 v108, v108
	v_fma_f32 v109, v109, s43, -v151
	v_exp_f32_e32 v109, v109
	s_waitcnt lgkmcnt(8)
	v_mfma_f32_32x32x16_bf16 v[16:31], v[244:247], v[96:99], v[16:31]
	v_fma_f32 v110, v110, s43, -v151
	v_exp_f32_e32 v110, v110
	v_fma_f32 v111, v111, s43, -v151
	v_exp_f32_e32 v111, v111
	v_add_f32_e32 v0, v0, v104
	v_add_f32_e32 v14, v14, v105
	v_add_f32_e32 v15, v15, v106
	v_add_f32_e32 v0, v0, v107
	v_cvt_pk_bf16_f32 v104, v104, v105
	v_cvt_pk_bf16_f32 v105, v106, v107
	v_cvt_pk_bf16_f32 v106, v108, v109
	v_cvt_pk_bf16_f32 v107, v110, v111
	v_add_f32_e32 v14, v14, v108
	v_add_f32_e32 v15, v15, v109
	v_add_f32_e32 v0, v0, v110
	v_add_f32_e32 v14, v14, v111
	s_waitcnt lgkmcnt(6)
	v_mfma_f32_32x32x16_bf16 v[64:79], v[156:159], v[104:107], v[64:79]
	ds_read_b64_tr_b16 v[2:3], v248 offset:16384
	ds_read_b64_tr_b16 v[4:5], v248 offset:18432
	ds_read_b64_tr_b16 v[6:7], v249 offset:16384
	ds_read_b64_tr_b16 v[8:9], v249 offset:18432
	ds_read_b64_tr_b16 v[10:11], v250 offset:16384
	ds_read_b64_tr_b16 v[12:13], v250 offset:18432
	ds_read_b64_tr_b16 v[244:245], v251 offset:16384
	ds_read_b64_tr_b16 v[246:247], v251 offset:18432
	v_fma_f32 v80, v80, s43, -v151
	v_exp_f32_e32 v80, v80
	v_fma_f32 v81, v81, s43, -v151
	v_exp_f32_e32 v81, v81
	s_waitcnt lgkmcnt(12)
	v_mfma_f32_32x32x16_bf16 v[48:63], v[160:163], v[104:107], v[48:63]
	v_fma_f32 v82, v82, s43, -v151
	v_exp_f32_e32 v82, v82
	v_fma_f32 v83, v83, s43, -v151
	v_exp_f32_e32 v83, v83
	s_waitcnt lgkmcnt(10)
	v_mfma_f32_32x32x16_bf16 v[32:47], v[252:255], v[104:107], v[32:47]
	v_fma_f32 v84, v84, s43, -v151
	v_exp_f32_e32 v84, v84
	v_fma_f32 v85, v85, s43, -v151
	v_exp_f32_e32 v85, v85
	s_waitcnt lgkmcnt(8)
	v_mfma_f32_32x32x16_bf16 v[16:31], v[100:103], v[104:107], v[16:31]
	v_fma_f32 v86, v86, s43, -v151
	v_exp_f32_e32 v86, v86
	v_fma_f32 v87, v87, s43, -v151
	v_exp_f32_e32 v87, v87
	v_add_f32_e32 v0, v0, v80
	v_add_f32_e32 v14, v14, v81
	v_add_f32_e32 v15, v15, v82
	v_add_f32_e32 v0, v0, v83
	v_cvt_pk_bf16_f32 v80, v80, v81
	v_cvt_pk_bf16_f32 v81, v82, v83
	v_cvt_pk_bf16_f32 v82, v84, v85
	v_cvt_pk_bf16_f32 v83, v86, v87
	v_add_f32_e32 v14, v14, v84
	v_add_f32_e32 v15, v15, v85
	v_add_f32_e32 v0, v0, v86
	v_add_f32_e32 v14, v14, v87
	s_waitcnt lgkmcnt(6)
	v_mfma_f32_32x32x16_bf16 v[64:79], v[2:5], v[80:83], v[64:79]
	ds_read_b64_tr_b16 v[156:157], v248 offset:20480
	ds_read_b64_tr_b16 v[158:159], v248 offset:22528
	ds_read_b64_tr_b16 v[160:161], v249 offset:20480
	ds_read_b64_tr_b16 v[162:163], v249 offset:22528
	ds_read_b64_tr_b16 v[252:253], v250 offset:20480
	ds_read_b64_tr_b16 v[254:255], v250 offset:22528
	ds_read_b64_tr_b16 v[100:101], v251 offset:20480
	ds_read_b64_tr_b16 v[102:103], v251 offset:22528
	v_fma_f32 v88, v88, s43, -v151
	v_exp_f32_e32 v88, v88
	v_fma_f32 v89, v89, s43, -v151
	v_exp_f32_e32 v89, v89
	s_waitcnt lgkmcnt(12)
	v_mfma_f32_32x32x16_bf16 v[48:63], v[6:9], v[80:83], v[48:63]
	v_fma_f32 v90, v90, s43, -v151
	v_exp_f32_e32 v90, v90
	v_fma_f32 v91, v91, s43, -v151
	v_exp_f32_e32 v91, v91
	s_waitcnt lgkmcnt(10)
	v_mfma_f32_32x32x16_bf16 v[32:47], v[10:13], v[80:83], v[32:47]
	v_fma_f32 v92, v92, s43, -v151
	v_exp_f32_e32 v92, v92
	v_fma_f32 v93, v93, s43, -v151
	v_exp_f32_e32 v93, v93
	s_waitcnt lgkmcnt(8)
	v_mfma_f32_32x32x16_bf16 v[16:31], v[244:247], v[80:83], v[16:31]
	v_fma_f32 v94, v94, s43, -v151
	v_exp_f32_e32 v94, v94
	v_fma_f32 v95, v95, s43, -v151
	v_exp_f32_e32 v95, v95
	v_add_f32_e32 v0, v0, v88
	v_add_f32_e32 v14, v14, v89
	v_add_f32_e32 v15, v15, v90
	v_add_f32_e32 v0, v0, v91
	v_cvt_pk_bf16_f32 v88, v88, v89
	v_cvt_pk_bf16_f32 v89, v90, v91
	v_cvt_pk_bf16_f32 v90, v92, v93
	v_cvt_pk_bf16_f32 v91, v94, v95
	v_add_f32_e32 v14, v14, v92
	v_add_f32_e32 v15, v15, v93
	v_add_f32_e32 v0, v0, v94
	v_add_f32_e32 v14, v14, v95
	s_waitcnt lgkmcnt(6)
	v_mfma_f32_32x32x16_bf16 v[64:79], v[156:159], v[88:91], v[64:79]
	s_waitcnt lgkmcnt(4)
	v_mfma_f32_32x32x16_bf16 v[48:63], v[160:163], v[88:91], v[48:63]
	s_waitcnt lgkmcnt(2)
	v_mfma_f32_32x32x16_bf16 v[32:47], v[252:255], v[88:91], v[32:47]
	s_waitcnt lgkmcnt(0)
	v_mfma_f32_32x32x16_bf16 v[16:31], v[100:103], v[88:91], v[16:31]
	v_add_f32_e32 v0, v0, v14
	v_add_f32_e32 v150, v150, v15
	v_add_f32_e32 v150, v150, v0

.LBB0_355:
	s_cmp_gt_i32 s63, s52
	s_cbranch_scc1 .LBB0_345
	s_and_b32 s38, s63, 3
	s_mulk_i32 s38, 0x6000
	s_add_i32 s38, s38, 0
	v_add3_u32 v14, s38, v174, v173
	v_add3_u32 v15, s38, v174, v177
	ds_read_b128 v[2:5], v14
	ds_read_b128 v[6:9], v14 offset:4096
	ds_read_b128 v[10:13], v15
	ds_read_b128 v[152:155], v15 offset:4096
	v_add3_u32 v14, s38, v174, v179
	v_add3_u32 v15, s38, v174, v180
	ds_read_b128 v[156:159], v14
	ds_read_b128 v[160:163], v14 offset:4096
	ds_read_b128 v[244:247], v15
	ds_read_b128 v[248:251], v15 offset:4096
	s_waitcnt lgkmcnt(6)
	v_mfma_f32_32x32x16_bf16 v[96:111], v[2:5], v[112:115], 0
	v_mfma_f32_32x32x16_bf16 v[80:95], v[6:9], v[112:115], 0
	s_waitcnt lgkmcnt(4)
	v_mfma_f32_32x32x16_bf16 v[96:111], v[10:13], v[116:119], v[96:111]
	v_mfma_f32_32x32x16_bf16 v[80:95], v[152:155], v[116:119], v[80:95]
	s_waitcnt lgkmcnt(2)
	v_mfma_f32_32x32x16_bf16 v[96:111], v[156:159], v[120:123], v[96:111]
	v_mfma_f32_32x32x16_bf16 v[80:95], v[160:163], v[120:123], v[80:95]
	s_waitcnt lgkmcnt(0)
	v_mfma_f32_32x32x16_bf16 v[80:95], v[248:251], v[124:127], v[80:95]
	v_mfma_f32_32x32x16_bf16 v[96:111], v[244:247], v[124:127], v[96:111]
	s_nop 10
	v_max3_f32 v0, v80, v81, v82
	v_max3_f32 v2, v83, v84, v85
	v_max3_f32 v3, v86, v87, v88
	v_max3_f32 v4, v89, v90, v91
	v_max3_f32 v0, v0, v92, v93
	v_max3_f32 v2, v2, v94, v95
	v_max3_f32 v3, v3, v96, v97
	v_max3_f32 v4, v4, v98, v99
	v_max3_f32 v0, v0, v100, v101
	v_max3_f32 v2, v2, v102, v103
	v_max3_f32 v3, v3, v104, v105
	v_max3_f32 v4, v4, v106, v107
	v_max3_f32 v0, v0, v108, v109
	v_max3_f32 v2, v2, v110, v111
	v_max3_f32 v0, v0, v3, v4
	v_max_f32_e32 v0, v0, v2
	v_mul_f32_e32 v0, 0x3e38aa3b, v0
	v_mov_b32_e32 v2, v0
	s_nop 1
	v_permlane32_swap_b32_e32 v0, v2
	v_max_f32_e32 v0, v0, v2
	v_add_f32_e32 v2, 0x41000000, v151
	v_cmp_gt_f32_e32 vcc, v0, v2
	s_cbranch_vccz .LBB0_344
	v_max_f32_e32 v0, v0, v0
	v_max_f32_e32 v2, v151, v151
	v_max_f32_e32 v2, v2, v0
	v_sub_f32_e32 v0, v151, v2
	v_exp_f32_e32 v0, v0
	v_mov_b32_e32 v151, v2
	v_pk_mul_f32 v[78:79], v[0:1], v[78:79] op_sel_hi:[0,1]
	v_pk_mul_f32 v[76:77], v[0:1], v[76:77] op_sel_hi:[0,1]
	v_pk_mul_f32 v[74:75], v[0:1], v[74:75] op_sel_hi:[0,1]
	v_pk_mul_f32 v[72:73], v[0:1], v[72:73] op_sel_hi:[0,1]
	v_pk_mul_f32 v[70:71], v[0:1], v[70:71] op_sel_hi:[0,1]
	v_pk_mul_f32 v[68:69], v[0:1], v[68:69] op_sel_hi:[0,1]
	v_pk_mul_f32 v[66:67], v[0:1], v[66:67] op_sel_hi:[0,1]
	v_pk_mul_f32 v[64:65], v[0:1], v[64:65] op_sel_hi:[0,1]
	v_pk_mul_f32 v[62:63], v[0:1], v[62:63] op_sel_hi:[0,1]
	v_pk_mul_f32 v[60:61], v[0:1], v[60:61] op_sel_hi:[0,1]
	v_pk_mul_f32 v[58:59], v[0:1], v[58:59] op_sel_hi:[0,1]
	v_pk_mul_f32 v[56:57], v[0:1], v[56:57] op_sel_hi:[0,1]
	v_pk_mul_f32 v[54:55], v[0:1], v[54:55] op_sel_hi:[0,1]
	v_pk_mul_f32 v[52:53], v[0:1], v[52:53] op_sel_hi:[0,1]
	v_pk_mul_f32 v[50:51], v[0:1], v[50:51] op_sel_hi:[0,1]
	v_pk_mul_f32 v[48:49], v[0:1], v[48:49] op_sel_hi:[0,1]
	v_pk_mul_f32 v[46:47], v[0:1], v[46:47] op_sel_hi:[0,1]
	v_pk_mul_f32 v[44:45], v[0:1], v[44:45] op_sel_hi:[0,1]
	v_pk_mul_f32 v[42:43], v[0:1], v[42:43] op_sel_hi:[0,1]
	v_pk_mul_f32 v[40:41], v[0:1], v[40:41] op_sel_hi:[0,1]
	v_pk_mul_f32 v[38:39], v[0:1], v[38:39] op_sel_hi:[0,1]
	v_pk_mul_f32 v[36:37], v[0:1], v[36:37] op_sel_hi:[0,1]
	v_pk_mul_f32 v[34:35], v[0:1], v[34:35] op_sel_hi:[0,1]
	v_pk_mul_f32 v[32:33], v[0:1], v[32:33] op_sel_hi:[0,1]
	v_pk_mul_f32 v[30:31], v[0:1], v[30:31] op_sel_hi:[0,1]
	v_pk_mul_f32 v[28:29], v[0:1], v[28:29] op_sel_hi:[0,1]
	v_pk_mul_f32 v[26:27], v[0:1], v[26:27] op_sel_hi:[0,1]
	v_pk_mul_f32 v[24:25], v[0:1], v[24:25] op_sel_hi:[0,1]
	v_pk_mul_f32 v[22:23], v[0:1], v[22:23] op_sel_hi:[0,1]
	v_pk_mul_f32 v[20:21], v[0:1], v[20:21] op_sel_hi:[0,1]
	v_pk_mul_f32 v[18:19], v[0:1], v[18:19] op_sel_hi:[0,1]
	v_pk_mul_f32 v[16:17], v[0:1], v[16:17] op_sel_hi:[0,1]
	v_mul_f32_e32 v150, v150, v0
	s_branch .LBB0_344

.LBB0_362:
	v_add3_u32 v248, s28, v199, v187
	v_add3_u32 v249, s28, v199, v190
	v_add3_u32 v250, s28, v199, v191
	v_add3_u32 v251, s28, v199, v192
	ds_read_b64_tr_b16 v[2:3], v248 offset:8192
	ds_read_b64_tr_b16 v[4:5], v248 offset:10240
	ds_read_b64_tr_b16 v[6:7], v249 offset:8192
	ds_read_b64_tr_b16 v[8:9], v249 offset:10240
	ds_read_b64_tr_b16 v[10:11], v250 offset:8192
	ds_read_b64_tr_b16 v[12:13], v250 offset:10240
	ds_read_b64_tr_b16 v[244:245], v251 offset:8192
	ds_read_b64_tr_b16 v[246:247], v251 offset:10240
	v_fma_f32 v96, v96, s43, -v150
	v_exp_f32_e32 v96, v96
	v_fma_f32 v97, v97, s43, -v150
	v_exp_f32_e32 v97, v97
	v_fma_f32 v98, v98, s43, -v150
	v_exp_f32_e32 v98, v98
	v_fma_f32 v99, v99, s43, -v150
	v_exp_f32_e32 v99, v99
	v_fma_f32 v100, v100, s43, -v150
	v_exp_f32_e32 v100, v100
	v_fma_f32 v101, v101, s43, -v150
	v_exp_f32_e32 v101, v101
	v_fma_f32 v102, v102, s43, -v150
	v_exp_f32_e32 v102, v102
	v_fma_f32 v103, v103, s43, -v150
	v_exp_f32_e32 v103, v103
	v_add_f32_e32 v0, v96, v97
	v_add_f32_e32 v14, v98, v99
	v_cvt_pk_bf16_f32 v96, v96, v97
	v_cvt_pk_bf16_f32 v97, v98, v99
	v_cvt_pk_bf16_f32 v98, v100, v101
	v_cvt_pk_bf16_f32 v99, v102, v103
	v_add_f32_e32 v15, v100, v101
	v_add_f32_e32 v0, v0, v102
	v_add_f32_e32 v14, v14, v103
	s_waitcnt lgkmcnt(6)
	v_mfma_f32_32x32x16_bf16 v[16:31], v[2:5], v[96:99], v[16:31]
	ds_read_b64_tr_b16 v[156:157], v248 offset:12288
	ds_read_b64_tr_b16 v[158:159], v248 offset:14336
	ds_read_b64_tr_b16 v[160:161], v249 offset:12288
	ds_read_b64_tr_b16 v[162:163], v249 offset:14336
	ds_read_b64_tr_b16 v[252:253], v250 offset:12288
	ds_read_b64_tr_b16 v[254:255], v250 offset:14336
	ds_read_b64_tr_b16 v[100:101], v251 offset:12288
	ds_read_b64_tr_b16 v[102:103], v251 offset:14336
	v_fma_f32 v104, v104, s43, -v150
	v_exp_f32_e32 v104, v104
	v_fma_f32 v105, v105, s43, -v150
	v_exp_f32_e32 v105, v105
	s_waitcnt lgkmcnt(12)
	v_mfma_f32_32x32x16_bf16 v[32:47], v[6:9], v[96:99], v[32:47]
	v_fma_f32 v106, v106, s43, -v150
	v_exp_f32_e32 v106, v106
	v_fma_f32 v107, v107, s43, -v150
	v_exp_f32_e32 v107, v107
	s_waitcnt lgkmcnt(10)
	v_mfma_f32_32x32x16_bf16 v[48:63], v[10:13], v[96:99], v[48:63]
	v_fma_f32 v108, v108, s43, -v150
	v_exp_f32_e32 v108, v108
	v_fma_f32 v109, v109, s43, -v150
	v_exp_f32_e32 v109, v109
	s_waitcnt lgkmcnt(8)
	v_mfma_f32_32x32x16_bf16 v[64:79], v[244:247], v[96:99], v[64:79]
	v_fma_f32 v110, v110, s43, -v150
	v_exp_f32_e32 v110, v110
	v_fma_f32 v111, v111, s43, -v150
	v_exp_f32_e32 v111, v111
	v_add_f32_e32 v0, v0, v104
	v_add_f32_e32 v14, v14, v105
	v_add_f32_e32 v15, v15, v106
	v_add_f32_e32 v0, v0, v107
	v_cvt_pk_bf16_f32 v104, v104, v105
	v_cvt_pk_bf16_f32 v105, v106, v107
	v_cvt_pk_bf16_f32 v106, v108, v109
	v_cvt_pk_bf16_f32 v107, v110, v111
	v_add_f32_e32 v14, v14, v108
	v_add_f32_e32 v15, v15, v109
	v_add_f32_e32 v0, v0, v110
	v_add_f32_e32 v14, v14, v111
	s_waitcnt lgkmcnt(6)
	v_mfma_f32_32x32x16_bf16 v[16:31], v[156:159], v[104:107], v[16:31]
	ds_read_b64_tr_b16 v[2:3], v248 offset:16384
	ds_read_b64_tr_b16 v[4:5], v248 offset:18432
	ds_read_b64_tr_b16 v[6:7], v249 offset:16384
	ds_read_b64_tr_b16 v[8:9], v249 offset:18432
	ds_read_b64_tr_b16 v[10:11], v250 offset:16384
	ds_read_b64_tr_b16 v[12:13], v250 offset:18432
	ds_read_b64_tr_b16 v[244:245], v251 offset:16384
	ds_read_b64_tr_b16 v[246:247], v251 offset:18432
	v_fma_f32 v80, v80, s43, -v150
	v_exp_f32_e32 v80, v80
	v_fma_f32 v81, v81, s43, -v150
	v_exp_f32_e32 v81, v81
	s_waitcnt lgkmcnt(12)
	v_mfma_f32_32x32x16_bf16 v[32:47], v[160:163], v[104:107], v[32:47]
	v_fma_f32 v82, v82, s43, -v150
	v_exp_f32_e32 v82, v82
	v_fma_f32 v83, v83, s43, -v150
	v_exp_f32_e32 v83, v83
	s_waitcnt lgkmcnt(10)
	v_mfma_f32_32x32x16_bf16 v[48:63], v[252:255], v[104:107], v[48:63]
	v_fma_f32 v84, v84, s43, -v150
	v_exp_f32_e32 v84, v84
	v_fma_f32 v85, v85, s43, -v150
	v_exp_f32_e32 v85, v85
	s_waitcnt lgkmcnt(8)
	v_mfma_f32_32x32x16_bf16 v[64:79], v[100:103], v[104:107], v[64:79]
	v_fma_f32 v86, v86, s43, -v150
	v_exp_f32_e32 v86, v86
	v_fma_f32 v87, v87, s43, -v150
	v_exp_f32_e32 v87, v87
	v_add_f32_e32 v0, v0, v80
	v_add_f32_e32 v14, v14, v81
	v_add_f32_e32 v15, v15, v82
	v_add_f32_e32 v0, v0, v83
	v_cvt_pk_bf16_f32 v80, v80, v81
	v_cvt_pk_bf16_f32 v81, v82, v83
	v_cvt_pk_bf16_f32 v82, v84, v85
	v_cvt_pk_bf16_f32 v83, v86, v87
	v_add_f32_e32 v14, v14, v84
	v_add_f32_e32 v15, v15, v85
	v_add_f32_e32 v0, v0, v86
	v_add_f32_e32 v14, v14, v87
	s_waitcnt lgkmcnt(6)
	v_mfma_f32_32x32x16_bf16 v[16:31], v[2:5], v[80:83], v[16:31]
	ds_read_b64_tr_b16 v[156:157], v248 offset:20480
	ds_read_b64_tr_b16 v[158:159], v248 offset:22528
	ds_read_b64_tr_b16 v[160:161], v249 offset:20480
	ds_read_b64_tr_b16 v[162:163], v249 offset:22528
	ds_read_b64_tr_b16 v[252:253], v250 offset:20480
	ds_read_b64_tr_b16 v[254:255], v250 offset:22528
	ds_read_b64_tr_b16 v[100:101], v251 offset:20480
	ds_read_b64_tr_b16 v[102:103], v251 offset:22528
	v_fma_f32 v88, v88, s43, -v150
	v_exp_f32_e32 v88, v88
	v_fma_f32 v89, v89, s43, -v150
	v_exp_f32_e32 v89, v89
	s_waitcnt lgkmcnt(12)
	v_mfma_f32_32x32x16_bf16 v[32:47], v[6:9], v[80:83], v[32:47]
	v_fma_f32 v90, v90, s43, -v150
	v_exp_f32_e32 v90, v90
	v_fma_f32 v91, v91, s43, -v150
	v_exp_f32_e32 v91, v91
	s_waitcnt lgkmcnt(10)
	v_mfma_f32_32x32x16_bf16 v[48:63], v[10:13], v[80:83], v[48:63]
	v_fma_f32 v92, v92, s43, -v150
	v_exp_f32_e32 v92, v92
	v_fma_f32 v93, v93, s43, -v150
	v_exp_f32_e32 v93, v93
	s_waitcnt lgkmcnt(8)
	v_mfma_f32_32x32x16_bf16 v[64:79], v[244:247], v[80:83], v[64:79]
	v_fma_f32 v94, v94, s43, -v150
	v_exp_f32_e32 v94, v94
	v_fma_f32 v95, v95, s43, -v150
	v_exp_f32_e32 v95, v95
	v_add_f32_e32 v0, v0, v88
	v_add_f32_e32 v14, v14, v89
	v_add_f32_e32 v15, v15, v90
	v_add_f32_e32 v0, v0, v91
	v_cvt_pk_bf16_f32 v88, v88, v89
	v_cvt_pk_bf16_f32 v89, v90, v91
	v_cvt_pk_bf16_f32 v90, v92, v93
	v_cvt_pk_bf16_f32 v91, v94, v95
	v_add_f32_e32 v14, v14, v92
	v_add_f32_e32 v15, v15, v93
	v_add_f32_e32 v0, v0, v94
	v_add_f32_e32 v14, v14, v95
	s_waitcnt lgkmcnt(6)
	v_mfma_f32_32x32x16_bf16 v[16:31], v[156:159], v[88:91], v[16:31]
	s_waitcnt lgkmcnt(4)
	v_mfma_f32_32x32x16_bf16 v[32:47], v[160:163], v[88:91], v[32:47]
	s_waitcnt lgkmcnt(2)
	v_mfma_f32_32x32x16_bf16 v[48:63], v[252:255], v[88:91], v[48:63]
	s_waitcnt lgkmcnt(0)
	v_mfma_f32_32x32x16_bf16 v[64:79], v[100:103], v[88:91], v[64:79]
	v_add_f32_e32 v0, v0, v14
	v_add_f32_e32 v154, v154, v15
	v_add_f32_e32 v154, v154, v0

.LBB0_373:
	s_cmp_gt_i32 s34, s52
	s_cbranch_scc1 .LBB0_363
	s_and_b32 s28, s34, 3
	s_mulk_i32 s28, 0x6000
	s_add_i32 s28, s28, 0
	v_add3_u32 v14, s28, v174, v173
	v_add3_u32 v15, s28, v174, v177
	ds_read_b128 v[2:5], v14
	ds_read_b128 v[6:9], v14 offset:4096
	ds_read_b128 v[10:13], v15
	ds_read_b128 v[252:255], v15 offset:4096
	v_add3_u32 v14, s28, v174, v179
	v_add3_u32 v15, s28, v174, v180
	ds_read_b128 v[156:159], v14
	ds_read_b128 v[160:163], v14 offset:4096
	ds_read_b128 v[244:247], v15
	ds_read_b128 v[248:251], v15 offset:4096
	s_waitcnt lgkmcnt(6)
	v_mfma_f32_32x32x16_bf16 v[96:111], v[2:5], v[112:115], 0
	v_mfma_f32_32x32x16_bf16 v[80:95], v[6:9], v[112:115], 0
	s_waitcnt lgkmcnt(4)
	v_mfma_f32_32x32x16_bf16 v[96:111], v[10:13], v[116:119], v[96:111]
	v_mfma_f32_32x32x16_bf16 v[80:95], v[252:255], v[116:119], v[80:95]
	s_waitcnt lgkmcnt(2)
	v_mfma_f32_32x32x16_bf16 v[96:111], v[156:159], v[120:123], v[96:111]
	v_mfma_f32_32x32x16_bf16 v[80:95], v[160:163], v[120:123], v[80:95]
	s_waitcnt lgkmcnt(0)
	v_mfma_f32_32x32x16_bf16 v[80:95], v[248:251], v[124:127], v[80:95]
	v_mfma_f32_32x32x16_bf16 v[96:111], v[244:247], v[124:127], v[96:111]
	s_nop 10
	v_max3_f32 v0, v80, v81, v82
	v_max3_f32 v2, v83, v84, v85
	v_max3_f32 v3, v86, v87, v88
	v_max3_f32 v4, v89, v90, v91
	v_max3_f32 v0, v0, v92, v93
	v_max3_f32 v2, v2, v94, v95
	v_max3_f32 v3, v3, v96, v97
	v_max3_f32 v4, v4, v98, v99
	v_max3_f32 v0, v0, v100, v101
	v_max3_f32 v2, v2, v102, v103
	v_max3_f32 v3, v3, v104, v105
	v_max3_f32 v4, v4, v106, v107
	v_max3_f32 v0, v0, v108, v109
	v_max3_f32 v2, v2, v110, v111
	v_max3_f32 v0, v0, v3, v4
	v_max_f32_e32 v0, v0, v2
	v_mul_f32_e32 v0, 0x3e38aa3b, v0
	v_mov_b32_e32 v2, v0
	s_nop 1
	v_permlane32_swap_b32_e32 v0, v2
	v_max_f32_e32 v0, v0, v2
	v_add_f32_e32 v2, 0x41000000, v150
	v_cmp_gt_f32_e32 vcc, v0, v2
	s_cbranch_vccz .LBB0_362
	v_max_f32_e32 v0, v0, v0
	v_max_f32_e32 v2, v150, v150
	v_max_f32_e32 v2, v2, v0
	v_sub_f32_e32 v0, v150, v2
	v_exp_f32_e32 v0, v0
	v_mov_b32_e32 v150, v2
	v_pk_mul_f32 v[30:31], v[30:31], v[0:1] op_sel_hi:[1,0]
	v_pk_mul_f32 v[28:29], v[28:29], v[0:1] op_sel_hi:[1,0]
	v_pk_mul_f32 v[26:27], v[26:27], v[0:1] op_sel_hi:[1,0]
	v_pk_mul_f32 v[24:25], v[24:25], v[0:1] op_sel_hi:[1,0]
	v_pk_mul_f32 v[22:23], v[22:23], v[0:1] op_sel_hi:[1,0]
	v_pk_mul_f32 v[20:21], v[20:21], v[0:1] op_sel_hi:[1,0]
	v_pk_mul_f32 v[18:19], v[18:19], v[0:1] op_sel_hi:[1,0]
	v_pk_mul_f32 v[16:17], v[16:17], v[0:1] op_sel_hi:[1,0]
	v_pk_mul_f32 v[46:47], v[46:47], v[0:1] op_sel_hi:[1,0]
	v_pk_mul_f32 v[44:45], v[44:45], v[0:1] op_sel_hi:[1,0]
	v_pk_mul_f32 v[42:43], v[42:43], v[0:1] op_sel_hi:[1,0]
	v_pk_mul_f32 v[40:41], v[40:41], v[0:1] op_sel_hi:[1,0]
	v_pk_mul_f32 v[38:39], v[38:39], v[0:1] op_sel_hi:[1,0]
	v_pk_mul_f32 v[36:37], v[36:37], v[0:1] op_sel_hi:[1,0]
	v_pk_mul_f32 v[34:35], v[34:35], v[0:1] op_sel_hi:[1,0]
	v_pk_mul_f32 v[32:33], v[32:33], v[0:1] op_sel_hi:[1,0]
	v_pk_mul_f32 v[62:63], v[62:63], v[0:1] op_sel_hi:[1,0]
	v_pk_mul_f32 v[60:61], v[60:61], v[0:1] op_sel_hi:[1,0]
	v_pk_mul_f32 v[58:59], v[58:59], v[0:1] op_sel_hi:[1,0]
	v_pk_mul_f32 v[56:57], v[56:57], v[0:1] op_sel_hi:[1,0]
	v_pk_mul_f32 v[54:55], v[54:55], v[0:1] op_sel_hi:[1,0]
	v_pk_mul_f32 v[52:53], v[52:53], v[0:1] op_sel_hi:[1,0]
	v_pk_mul_f32 v[50:51], v[50:51], v[0:1] op_sel_hi:[1,0]
	v_pk_mul_f32 v[48:49], v[48:49], v[0:1] op_sel_hi:[1,0]
	v_pk_mul_f32 v[78:79], v[78:79], v[0:1] op_sel_hi:[1,0]
	v_pk_mul_f32 v[76:77], v[76:77], v[0:1] op_sel_hi:[1,0]
	v_pk_mul_f32 v[74:75], v[74:75], v[0:1] op_sel_hi:[1,0]
	v_pk_mul_f32 v[72:73], v[72:73], v[0:1] op_sel_hi:[1,0]
	v_pk_mul_f32 v[70:71], v[70:71], v[0:1] op_sel_hi:[1,0]
	v_pk_mul_f32 v[68:69], v[68:69], v[0:1] op_sel_hi:[1,0]
	v_pk_mul_f32 v[66:67], v[66:67], v[0:1] op_sel_hi:[1,0]
	v_pk_mul_f32 v[64:65], v[64:65], v[0:1] op_sel_hi:[1,0]
	v_mul_f32_e32 v154, v154, v0
	s_branch .LBB0_362
